# retention scan epilogue: final state tile transposed inside lane quads (DPP quad_perm + v_cndmask) and stored as 8 x 16-byte-per-lane stores instead of 32 dword stores
# speedup vs baseline: 1.0019x; 1.0019x over previous
.LBB0_1313:
	s_or_b64 exec, exec, s[0:1]
	s_add_u32 s6, s94, 0x2a402800
	s_addc_u32 s7, s95, 0
	s_cmpk_gt_u32 s2, 0x7f
	s_waitcnt lgkmcnt(0)
	s_barrier
	s_cbranch_scc1 .LBB0_1326
	s_and_b32 s76, s2, 7
	s_lshr_b32 s77, s2, 3
	s_lshr_b32 s78, s77, 3
	s_lshl_b32 s72, s76, 1
	s_add_u32 s72, s72, s78
	s_and_b32 s73, s77, 7
	s_lshr_b32 s74, s72, 2
	s_and_b32 s75, s72, 3
	s_mov_b32 s82, 0xbd020aec
	s_cmp_eq_u32 s75, 1
	s_cselect_b32 s82, 0xbc8102b3, s82
	s_cmp_eq_u32 s75, 2
	s_cselect_b32 s82, 0xbc0080ac, s82
	s_cmp_eq_u32 s75, 3
	s_cselect_b32 s82, 0xbb80402b, s82
	v_lshrrev_b32_e32 v210, 6, v198
	v_and_b32_e32 v211, 15, v198
	v_bfe_u32 v212, v198, 4, 2
	v_readfirstlane_b32 s71, v210
	v_lshl_or_b32 v213, v210, 4, v211
	v_add_u32_e32 v213, 1, v213
	v_cvt_f32_i32_e32 v213, v213
	v_mul_f32_e32 v213, s82, v213
	v_mul_f32_e32 v213, 0x3fb8aa3b, v213
	v_exp_f32_e32 v202, v213
	v_mov_b32_e32 v213, 0x43000000
	v_mul_f32_e32 v213, s82, v213
	v_mul_f32_e32 v213, 0x3fb8aa3b, v213
	v_exp_f32_e32 v204, v213
	s_nop 1
	v_mov_b32_e32 v203, v202
	v_mov_b32_e32 v205, v204
	v_lshlrev_b32_e32 v192, 4, v211
	v_lshl_add_u32 v192, v212, 8, v192
	v_lshlrev_b32_e32 v193, 11, v211
	v_lshl_add_u32 v193, v212, 4, v193
	v_and_b32_e32 v213, 63, v198
	v_lshrrev_b32_e32 v195, 3, v213
	v_and_b32_e32 v215, 7, v213
	v_mul_u32_u24_e32 v214, 144, v195
	v_lshl_add_u32 v215, v215, 4, v214
	v_and_b32_e32 v214, 7, v213
	v_lshlrev_b32_e32 v195, 12, v195
	v_lshl_add_u32 v195, v214, 4, v195
	v_add_u32_e32 v220, 0x8000, v195
	v_mul_u32_u24_e32 v214, 144, v211
	v_lshl_add_u32 v214, v212, 3, v214
	v_mul_u32_u24_e32 v213, 2304, v210
	v_add_u32_e32 v213, 102400, v213
	v_add_u32_e32 v214, v214, v213
	v_add_u32_e32 v215, v215, v213
	v_lshrrev_b32_e32 v213, 3, v198
	v_and_b32_e32 v194, 7, v198
	v_lshlrev_b32_e32 v194, 4, v194
	v_lshrrev_b32_e32 v218, 2, v213
	v_lshrrev_b32_e32 v219, 3, v213
	v_xor_b32_e32 v218, v218, v219
	v_and_b32_e32 v218, 1, v218
	v_and_b32_e32 v219, 7, v198
	v_xor_b32_e32 v219, v219, v218
	v_mul_u32_u24_e32 v201, 272, v213
	v_lshl_add_u32 v201, v219, 4, v201
	v_lshrrev_b32_e32 v216, 2, v211
	v_lshrrev_b32_e32 v217, 3, v211
	v_xor_b32_e32 v216, v216, v217
	v_and_b32_e32 v216, 1, v216
	v_xor_b32_e32 v217, v212, v216
	v_lshlrev_b32_e32 v218, 3, v212
	v_lshlrev_b32_e32 v216, 4, v216
	v_xor_b32_e32 v218, v218, v216
	v_lshl_add_u32 v194, v213, 13, v194
	v_add_u32_e32 v201, 67584, v201
	v_mul_u32_u24_e32 v196, 528, v211
	v_add_u32_e32 v200, v218, v196
	v_lshl_add_u32 v200, v210, 6, v200
	v_add_u32_e32 v200, 33792, v200
	v_lshl_add_u32 v196, v217, 4, v196
	v_mul_u32_u24_e32 v197, 272, v211
	v_lshl_add_u32 v197, v217, 4, v197
	v_add_u32_e32 v197, 67584, v197
	v_lshlrev_b32_e32 v206, 13, v212
	v_and_b32_e32 v207, 3, v211
	v_lshl_add_u32 v206, v207, 6, v206
	v_lshrrev_b32_e32 v207, 2, v211
	v_lshl_add_u32 v206, v207, 4, v206
	v_add_u32_e32 v207, 2048, v206
	v_add_u32_e32 v208, 4096, v206
	v_add_u32_e32 v209, 6144, v206
	s_mov_b32 s76, 0x27402800
	s_lshl_b32 s77, s72, 20
	s_add_u32 s76, s76, s77
	s_lshl_b32 s77, s71, 12
	s_add_u32 s76, s76, s77
	s_add_u32 s62, s94, s76
	s_addc_u32 s63, s95, 0
	s_mov_b32 s76, 0x28403800
	s_lshl_b32 s77, s72, 21
	s_add_u32 s76, s76, s77
	s_lshl_b32 s77, s71, 13
	s_add_u32 s76, s76, s77
	s_add_u32 s64, s94, s76
	s_addc_u32 s65, s95, 0
	s_mov_b32 s76, 0x1a802800
	s_lshl_b32 s77, s74, 23
	s_add_u32 s76, s76, s77
	s_lshl_b32 s77, s71, 15
	s_add_u32 s76, s76, s77
	s_lshl_b32 s77, s75, 9
	s_add_u32 s76, s76, s77
	s_add_u32 s60, s94, s76
	s_addc_u32 s61, s95, 0
	s_mov_b32 s76, 0x23002800
	s_lshl_b32 s77, s72, 22
	s_add_u32 s76, s76, s77
	s_lshl_b32 s77, s73, 19
	s_add_u32 s76, s76, s77
	s_add_u32 s66, s94, s76
	s_addc_u32 s67, s95, 0
	s_mov_b32 s76, 0x2a402800
	s_lshl_b32 s77, s74, 24
	s_add_u32 s76, s76, s77
	s_lshl_b32 s77, s71, 16
	s_add_u32 s76, s76, s77
	s_lshl_b32 s77, s75, 10
	s_add_u32 s76, s76, s77
	s_lshl_b32 s77, s73, 7
	s_add_u32 s76, s76, s77
	s_add_u32 s68, s94, s76
	s_addc_u32 s69, s95, 0
	s_mov_b32 s76, 0x6500000
	s_lshl_b32 s77, s72, 19
	s_add_u32 s76, s76, s77
	s_lshl_b32 s77, s71, 16
	s_add_u32 s76, s76, s77
	s_lshl_b32 s77, s73, 8
	s_add_u32 s76, s76, s77
	s_add_u32 s44, s92, s76
	s_addc_u32 s45, s93, 0
	s_add_u32 s46, s44, 0x8000
	s_addc_u32 s47, s45, 0
	global_load_dwordx4 v[176:179], v194, s[66:67]
	global_load_dwordx4 v[180:183], v194, s[66:67] offset:128
	global_load_dwordx4 v[0:3], v193, s[60:61]
	global_load_dwordx4 v[4:7], v193, s[60:61] offset:64
	global_load_dwordx4 v[8:11], v193, s[60:61] offset:128
	global_load_dwordx4 v[12:15], v193, s[60:61] offset:192
	global_load_dwordx4 v[16:19], v193, s[60:61] offset:256
	global_load_dwordx4 v[20:23], v193, s[60:61] offset:320
	global_load_dwordx4 v[24:27], v193, s[60:61] offset:384
	global_load_dwordx4 v[28:31], v193, s[60:61] offset:448
	global_load_dwordx4 v[32:35], v192, s[62:63]
	global_load_dwordx4 v[36:39], v192, s[62:63] offset:1024
	global_load_dwordx4 v[40:43], v192, s[62:63] offset:2048
	global_load_dwordx4 v[44:47], v192, s[62:63] offset:3072
	global_load_dwordx4 v[48:51], v192, s[64:65] offset:-4096
	global_load_dwordx4 v[64:67], v192, s[64:65]
	global_load_dwordx4 v[52:55], v192, s[64:65] offset:-3072
	global_load_dwordx4 v[68:71], v192, s[64:65] offset:1024
	global_load_dwordx4 v[56:59], v192, s[64:65] offset:-2048
	global_load_dwordx4 v[72:75], v192, s[64:65] offset:2048
	global_load_dwordx4 v[60:63], v192, s[64:65] offset:-1024
	global_load_dwordx4 v[76:79], v192, s[64:65] offset:3072
	v_mov_b32_e32 v216, 0
	v_mov_b32_e32 v217, 0
	v_mov_b32_e32 v218, 0
	v_mov_b32_e32 v219, 0
	v_mov_b32_e32 v80, 0
	v_mov_b32_e32 v81, 0
	v_mov_b32_e32 v82, 0
	v_mov_b32_e32 v83, 0
	v_mov_b32_e32 v84, 0
	v_mov_b32_e32 v85, 0
	v_mov_b32_e32 v86, 0
	v_mov_b32_e32 v87, 0
	v_mov_b32_e32 v88, 0
	v_mov_b32_e32 v89, 0
	v_mov_b32_e32 v90, 0
	v_mov_b32_e32 v91, 0
	v_mov_b32_e32 v92, 0
	v_mov_b32_e32 v93, 0
	v_mov_b32_e32 v94, 0
	v_mov_b32_e32 v95, 0
	v_mov_b32_e32 v96, 0
	v_mov_b32_e32 v97, 0
	v_mov_b32_e32 v98, 0
	v_mov_b32_e32 v99, 0
	v_mov_b32_e32 v100, 0
	v_mov_b32_e32 v101, 0
	v_mov_b32_e32 v102, 0
	v_mov_b32_e32 v103, 0
	v_mov_b32_e32 v104, 0
	v_mov_b32_e32 v105, 0
	v_mov_b32_e32 v106, 0
	v_mov_b32_e32 v107, 0
	v_mov_b32_e32 v108, 0
	v_mov_b32_e32 v109, 0
	v_mov_b32_e32 v110, 0
	v_mov_b32_e32 v111, 0
	v_lshlrev_b32_e32 v213, 4, v198
	ds_write_b128 v213, v[216:219] offset:0
	ds_write_b128 v213, v[216:219] offset:8192
	ds_write_b128 v213, v[216:219] offset:16384
	ds_write_b128 v213, v[216:219] offset:24576
	ds_write_b128 v213, v[216:219] offset:32768
	s_waitcnt vmcnt(20)
	ds_write_b128 v201, v[176:179]
	ds_write_b128 v201, v[180:183] offset:128
	v_add_u32_e32 v201, 17408, v201
	s_add_u32 s60, s60, 0x40000
	s_addc_u32 s61, s61, 0
	s_add_u32 s62, s62, 0x8000
	s_addc_u32 s63, s63, 0
	s_add_u32 s64, s64, 0x10000
	s_addc_u32 s65, s65, 0
	s_add_u32 s66, s66, 0x100
	s_addc_u32 s67, s67, 0
	global_load_dwordx4 v[230:233], v193, s[60:61]
	global_load_dwordx4 v[234:237], v193, s[60:61] offset:64
	global_load_dwordx4 v[238:241], v193, s[60:61] offset:128
	global_load_dwordx4 v[242:245], v193, s[60:61] offset:192
	global_load_dwordx4 v[246:249], v193, s[60:61] offset:256
	global_load_dwordx4 v[250:253], v193, s[60:61] offset:320
	global_load_dwordx4 v[184:187], v193, s[60:61] offset:384
	global_load_dwordx4 v[188:191], v193, s[60:61] offset:448
	global_load_dwordx4 v[128:131], v192, s[62:63]
	global_load_dwordx4 v[132:135], v192, s[62:63] offset:1024
	global_load_dwordx4 v[136:139], v192, s[62:63] offset:2048
	global_load_dwordx4 v[140:143], v192, s[62:63] offset:3072
	s_add_u32 s60, s60, 0x40000
	s_addc_u32 s61, s61, 0
	s_add_u32 s62, s62, 0x8000
	s_addc_u32 s63, s63, 0
	global_load_dwordx4 v[222:225], v194, s[66:67]
	global_load_dwordx4 v[226:229], v194, s[66:67] offset:128
	s_add_u32 s66, s66, 0x100
	s_addc_u32 s67, s67, 0
	s_mov_b32 s70, 0
	s_mov_b32 s80, 33792
	s_mov_b32 s81, 17408
	s_waitcnt vmcnt(0) lgkmcnt(0)
	s_barrier
	s_cmp_lt_u32 s71, 4
	s_cbranch_scc1 .Lscan_noprio
	s_setprio 1
.Lscan_noprio:
.Lscan_chunk:
	global_load_dwordx4 v[176:179], v194, s[66:67]
	global_load_dwordx4 v[180:183], v194, s[66:67] offset:128
	ds_read_b128 v[144:147], v196 offset:0
	ds_read_b128 v[148:151], v196 offset:8448
	ds_read_b128 v[152:155], v196 offset:16896
	ds_read_b128 v[156:159], v196 offset:25344
	ds_read_b128 v[160:163], v196 offset:64
	ds_read_b128 v[164:167], v196 offset:8512
	ds_read_b128 v[168:171], v196 offset:16960
	s_waitcnt lgkmcnt(6)
	s_waitcnt vmcnt(47)
	v_mfma_f32_16x16x32_bf16 v[112:115], v[144:147], v[0:3], 0
	ds_read_b128 v[172:175], v196 offset:25408
	s_waitcnt lgkmcnt(6)
	v_mfma_f32_16x16x32_bf16 v[116:119], v[148:151], v[0:3], 0
	ds_read_b128 v[144:147], v196 offset:128
	s_waitcnt lgkmcnt(6)
	v_mfma_f32_16x16x32_bf16 v[120:123], v[152:155], v[0:3], 0
	ds_read_b128 v[148:151], v196 offset:8576
	s_waitcnt lgkmcnt(6)
	v_mfma_f32_16x16x32_bf16 v[124:127], v[156:159], v[0:3], 0
	global_load_dwordx4 v[0:3], v193, s[60:61]
	ds_read_b128 v[152:155], v196 offset:17024
	s_waitcnt lgkmcnt(6)
	s_waitcnt vmcnt(47)
	v_mfma_f32_16x16x32_bf16 v[112:115], v[160:163], v[4:7], v[112:115]
	ds_read_b128 v[156:159], v196 offset:25472
	s_waitcnt lgkmcnt(6)
	v_mfma_f32_16x16x32_bf16 v[116:119], v[164:167], v[4:7], v[116:119]
	ds_read_b128 v[160:163], v196 offset:192
	s_waitcnt lgkmcnt(6)
	v_mfma_f32_16x16x32_bf16 v[120:123], v[168:171], v[4:7], v[120:123]
	ds_read_b128 v[164:167], v196 offset:8640
	s_waitcnt lgkmcnt(6)
	v_mfma_f32_16x16x32_bf16 v[124:127], v[172:175], v[4:7], v[124:127]
	global_load_dwordx4 v[4:7], v193, s[60:61] offset:64
	ds_read_b128 v[168:171], v196 offset:17088
	s_waitcnt lgkmcnt(6)
	s_waitcnt vmcnt(47)
	v_mfma_f32_16x16x32_bf16 v[112:115], v[144:147], v[8:11], v[112:115]
	ds_read_b128 v[172:175], v196 offset:25536
	s_waitcnt lgkmcnt(6)
	v_mfma_f32_16x16x32_bf16 v[116:119], v[148:151], v[8:11], v[116:119]
	ds_read_b128 v[144:147], v196 offset:256
	s_waitcnt lgkmcnt(6)
	v_mfma_f32_16x16x32_bf16 v[120:123], v[152:155], v[8:11], v[120:123]
	ds_read_b128 v[148:151], v196 offset:8704
	s_waitcnt lgkmcnt(6)
	v_mfma_f32_16x16x32_bf16 v[124:127], v[156:159], v[8:11], v[124:127]
	global_load_dwordx4 v[8:11], v193, s[60:61] offset:128
	ds_read_b128 v[152:155], v196 offset:17152
	s_waitcnt lgkmcnt(6)
	s_waitcnt vmcnt(47)
	v_mfma_f32_16x16x32_bf16 v[112:115], v[160:163], v[12:15], v[112:115]
	ds_read_b128 v[156:159], v196 offset:25600
	s_waitcnt lgkmcnt(6)
	v_mfma_f32_16x16x32_bf16 v[116:119], v[164:167], v[12:15], v[116:119]
	ds_read_b128 v[160:163], v196 offset:320
	s_waitcnt lgkmcnt(6)
	v_mfma_f32_16x16x32_bf16 v[120:123], v[168:171], v[12:15], v[120:123]
	ds_read_b128 v[164:167], v196 offset:8768
	s_waitcnt lgkmcnt(6)
	v_mfma_f32_16x16x32_bf16 v[124:127], v[172:175], v[12:15], v[124:127]
	global_load_dwordx4 v[12:15], v193, s[60:61] offset:192
	ds_read_b128 v[168:171], v196 offset:17216
	s_waitcnt lgkmcnt(6)
	s_waitcnt vmcnt(47)
	v_mfma_f32_16x16x32_bf16 v[112:115], v[144:147], v[16:19], v[112:115]
	ds_read_b128 v[172:175], v196 offset:25664
	s_waitcnt lgkmcnt(6)
	v_mfma_f32_16x16x32_bf16 v[116:119], v[148:151], v[16:19], v[116:119]
	ds_read_b128 v[144:147], v196 offset:384
	s_waitcnt lgkmcnt(6)
	v_mfma_f32_16x16x32_bf16 v[120:123], v[152:155], v[16:19], v[120:123]
	ds_read_b128 v[148:151], v196 offset:8832
	s_waitcnt lgkmcnt(6)
	v_mfma_f32_16x16x32_bf16 v[124:127], v[156:159], v[16:19], v[124:127]
	global_load_dwordx4 v[16:19], v193, s[60:61] offset:256
	ds_read_b128 v[152:155], v196 offset:17280
	s_waitcnt lgkmcnt(6)
	s_waitcnt vmcnt(47)
	v_mfma_f32_16x16x32_bf16 v[112:115], v[160:163], v[20:23], v[112:115]
	ds_read_b128 v[156:159], v196 offset:25728
	s_waitcnt lgkmcnt(6)
	v_mfma_f32_16x16x32_bf16 v[116:119], v[164:167], v[20:23], v[116:119]
	ds_read_b128 v[160:163], v196 offset:448
	s_waitcnt lgkmcnt(6)
	v_mfma_f32_16x16x32_bf16 v[120:123], v[168:171], v[20:23], v[120:123]
	ds_read_b128 v[164:167], v196 offset:8896
	s_waitcnt lgkmcnt(6)
	v_mfma_f32_16x16x32_bf16 v[124:127], v[172:175], v[20:23], v[124:127]
	global_load_dwordx4 v[20:23], v193, s[60:61] offset:320
	ds_read_b128 v[168:171], v196 offset:17344
	s_waitcnt lgkmcnt(6)
	s_waitcnt vmcnt(47)
	v_mfma_f32_16x16x32_bf16 v[112:115], v[144:147], v[24:27], v[112:115]
	ds_read_b128 v[172:175], v196 offset:25792
	s_waitcnt lgkmcnt(6)
	v_mfma_f32_16x16x32_bf16 v[116:119], v[148:151], v[24:27], v[116:119]
	s_waitcnt lgkmcnt(5)
	v_mfma_f32_16x16x32_bf16 v[120:123], v[152:155], v[24:27], v[120:123]
	s_waitcnt lgkmcnt(4)
	v_mfma_f32_16x16x32_bf16 v[124:127], v[156:159], v[24:27], v[124:127]
	global_load_dwordx4 v[24:27], v193, s[60:61] offset:384
	s_waitcnt lgkmcnt(3)
	s_waitcnt vmcnt(47)
	v_mfma_f32_16x16x32_bf16 v[112:115], v[160:163], v[28:31], v[112:115]
	s_waitcnt lgkmcnt(2)
	v_mfma_f32_16x16x32_bf16 v[116:119], v[164:167], v[28:31], v[116:119]
	s_waitcnt lgkmcnt(1)
	v_mfma_f32_16x16x32_bf16 v[120:123], v[168:171], v[28:31], v[120:123]
	s_waitcnt lgkmcnt(0)
	v_mfma_f32_16x16x32_bf16 v[124:127], v[172:175], v[28:31], v[124:127]
	global_load_dwordx4 v[28:31], v193, s[60:61] offset:448
	s_nop 7
	v_pk_mul_f32 v[112:113], v[112:113], v[202:203]
	v_pk_mul_f32 v[114:115], v[114:115], v[202:203]
	v_pk_mul_f32 v[116:117], v[116:117], v[202:203]
	v_pk_mul_f32 v[118:119], v[118:119], v[202:203]
	v_pk_mul_f32 v[120:121], v[120:121], v[202:203]
	v_pk_mul_f32 v[122:123], v[122:123], v[202:203]
	v_pk_mul_f32 v[124:125], v[124:125], v[202:203]
	v_pk_mul_f32 v[126:127], v[126:127], v[202:203]
	ds_read_b128 v[144:147], v197 offset:0
	ds_read_b128 v[148:151], v197 offset:4352
	ds_read_b128 v[152:155], v197 offset:8704
	ds_read_b128 v[156:159], v197 offset:13056
	ds_read_b128 v[160:163], v197 offset:64
	ds_read_b128 v[164:167], v197 offset:4416
	ds_read_b128 v[168:171], v197 offset:8768
	s_waitcnt lgkmcnt(6)
	s_waitcnt vmcnt(47)
	v_mfma_f32_16x16x32_bf16 v[112:115], v[144:147], v[32:35], v[112:115]
	ds_read_b128 v[172:175], v197 offset:13120
	s_waitcnt lgkmcnt(6)
	v_mfma_f32_16x16x32_bf16 v[116:119], v[148:151], v[32:35], v[116:119]
	ds_read_b128 v[144:147], v197 offset:128
	s_waitcnt lgkmcnt(6)
	v_mfma_f32_16x16x32_bf16 v[120:123], v[152:155], v[32:35], v[120:123]
	ds_read_b128 v[148:151], v197 offset:4480
	s_waitcnt lgkmcnt(6)
	v_mfma_f32_16x16x32_bf16 v[124:127], v[156:159], v[32:35], v[124:127]
	global_load_dwordx4 v[32:35], v192, s[62:63]
	ds_read_b128 v[152:155], v197 offset:8832
	s_waitcnt lgkmcnt(6)
	s_waitcnt vmcnt(47)
	v_mfma_f32_16x16x32_bf16 v[112:115], v[160:163], v[36:39], v[112:115]
	ds_read_b128 v[156:159], v197 offset:13184
	s_waitcnt lgkmcnt(6)
	v_mfma_f32_16x16x32_bf16 v[116:119], v[164:167], v[36:39], v[116:119]
	ds_read_b128 v[160:163], v197 offset:192
	s_waitcnt lgkmcnt(6)
	v_mfma_f32_16x16x32_bf16 v[120:123], v[168:171], v[36:39], v[120:123]
	ds_read_b128 v[164:167], v197 offset:4544
	s_waitcnt lgkmcnt(6)
	v_mfma_f32_16x16x32_bf16 v[124:127], v[172:175], v[36:39], v[124:127]
	global_load_dwordx4 v[36:39], v192, s[62:63] offset:1024
	ds_read_b128 v[168:171], v197 offset:8896
	s_waitcnt lgkmcnt(6)
	s_waitcnt vmcnt(47)
	v_mfma_f32_16x16x32_bf16 v[112:115], v[144:147], v[40:43], v[112:115]
	ds_read_b128 v[172:175], v197 offset:13248
	s_waitcnt lgkmcnt(6)
	v_mfma_f32_16x16x32_bf16 v[116:119], v[148:151], v[40:43], v[116:119]
	s_waitcnt lgkmcnt(5)
	v_mfma_f32_16x16x32_bf16 v[120:123], v[152:155], v[40:43], v[120:123]
	s_waitcnt lgkmcnt(4)
	v_mfma_f32_16x16x32_bf16 v[124:127], v[156:159], v[40:43], v[124:127]
	global_load_dwordx4 v[40:43], v192, s[62:63] offset:2048
	s_waitcnt lgkmcnt(3)
	s_waitcnt vmcnt(47)
	v_mfma_f32_16x16x32_bf16 v[112:115], v[160:163], v[44:47], v[112:115]
	s_waitcnt lgkmcnt(2)
	v_mfma_f32_16x16x32_bf16 v[116:119], v[164:167], v[44:47], v[116:119]
	s_waitcnt lgkmcnt(1)
	v_mfma_f32_16x16x32_bf16 v[120:123], v[168:171], v[44:47], v[120:123]
	s_waitcnt lgkmcnt(0)
	v_mfma_f32_16x16x32_bf16 v[124:127], v[172:175], v[44:47], v[124:127]
	global_load_dwordx4 v[44:47], v192, s[62:63] offset:3072
	s_nop 7
	v_cvt_pk_bf16_f32 v160, v112, v113
	v_cvt_pk_bf16_f32 v161, v114, v115
	v_cvt_pk_bf16_f32 v162, v116, v117
	v_cvt_pk_bf16_f32 v163, v118, v119
	v_cvt_pk_bf16_f32 v164, v120, v121
	v_cvt_pk_bf16_f32 v165, v122, v123
	v_cvt_pk_bf16_f32 v166, v124, v125
	v_cvt_pk_bf16_f32 v167, v126, v127
	ds_write_b64 v214, v[160:161]
	ds_write_b64 v214, v[162:163] offset:32
	ds_write_b64 v214, v[164:165] offset:64
	ds_write_b64 v214, v[166:167] offset:96
	s_waitcnt lgkmcnt(0)
	ds_read_b128 v[144:147], v215
	ds_read_b128 v[148:151], v215 offset:1152
	s_waitcnt lgkmcnt(0)
	global_store_dwordx4 v195, v[144:147], s[68:69]
	global_store_dwordx4 v220, v[148:151], s[68:69]
	v_pk_mul_f32 v[80:81], v[80:81], v[204:205]
	v_pk_mul_f32 v[82:83], v[82:83], v[204:205]
	v_pk_mul_f32 v[84:85], v[84:85], v[204:205]
	v_pk_mul_f32 v[86:87], v[86:87], v[204:205]
	v_pk_mul_f32 v[88:89], v[88:89], v[204:205]
	v_pk_mul_f32 v[90:91], v[90:91], v[204:205]
	v_pk_mul_f32 v[92:93], v[92:93], v[204:205]
	v_pk_mul_f32 v[94:95], v[94:95], v[204:205]
	v_pk_mul_f32 v[96:97], v[96:97], v[204:205]
	v_pk_mul_f32 v[98:99], v[98:99], v[204:205]
	v_pk_mul_f32 v[100:101], v[100:101], v[204:205]
	v_pk_mul_f32 v[102:103], v[102:103], v[204:205]
	v_pk_mul_f32 v[104:105], v[104:105], v[204:205]
	v_pk_mul_f32 v[106:107], v[106:107], v[204:205]
	v_pk_mul_f32 v[108:109], v[108:109], v[204:205]
	v_pk_mul_f32 v[110:111], v[110:111], v[204:205]
	ds_read_b128 v[144:147], v197 offset:0
	ds_read_b128 v[148:151], v197 offset:4352
	ds_read_b128 v[152:155], v197 offset:8704
	ds_read_b128 v[156:159], v197 offset:13056
	ds_read_b128 v[160:163], v197 offset:64
	ds_read_b128 v[164:167], v197 offset:4416
	ds_read_b128 v[168:171], v197 offset:8768
	s_waitcnt lgkmcnt(6)
	s_waitcnt vmcnt(22)
	v_mfma_f32_16x16x32_bf16 v[80:83], v[48:51], v[144:147], v[80:83]
	v_mfma_f32_16x16x32_bf16 v[96:99], v[64:67], v[144:147], v[96:99]
	ds_read_b128 v[172:175], v197 offset:13120
	s_waitcnt lgkmcnt(6)
	v_mfma_f32_16x16x32_bf16 v[84:87], v[48:51], v[148:151], v[84:87]
	v_mfma_f32_16x16x32_bf16 v[100:103], v[64:67], v[148:151], v[100:103]
	ds_read_b128 v[144:147], v197 offset:128
	s_waitcnt lgkmcnt(6)
	v_mfma_f32_16x16x32_bf16 v[88:91], v[48:51], v[152:155], v[88:91]
	v_mfma_f32_16x16x32_bf16 v[104:107], v[64:67], v[152:155], v[104:107]
	ds_read_b128 v[148:151], v197 offset:4480
	s_waitcnt lgkmcnt(6)
	v_mfma_f32_16x16x32_bf16 v[92:95], v[48:51], v[156:159], v[92:95]
	v_mfma_f32_16x16x32_bf16 v[108:111], v[64:67], v[156:159], v[108:111]
	global_load_dwordx4 v[48:51], v192, s[64:65] offset:-4096
	global_load_dwordx4 v[64:67], v192, s[64:65]
	ds_read_b128 v[152:155], v197 offset:8832
	s_waitcnt lgkmcnt(6)
	s_waitcnt vmcnt(22)
	v_mfma_f32_16x16x32_bf16 v[80:83], v[52:55], v[160:163], v[80:83]
	v_mfma_f32_16x16x32_bf16 v[96:99], v[68:71], v[160:163], v[96:99]
	ds_read_b128 v[156:159], v197 offset:13184
	s_waitcnt lgkmcnt(6)
	v_mfma_f32_16x16x32_bf16 v[84:87], v[52:55], v[164:167], v[84:87]
	v_mfma_f32_16x16x32_bf16 v[100:103], v[68:71], v[164:167], v[100:103]
	ds_read_b128 v[160:163], v197 offset:192
	s_waitcnt lgkmcnt(6)
	v_mfma_f32_16x16x32_bf16 v[88:91], v[52:55], v[168:171], v[88:91]
	v_mfma_f32_16x16x32_bf16 v[104:107], v[68:71], v[168:171], v[104:107]
	ds_read_b128 v[164:167], v197 offset:4544
	s_waitcnt lgkmcnt(6)
	v_mfma_f32_16x16x32_bf16 v[92:95], v[52:55], v[172:175], v[92:95]
	v_mfma_f32_16x16x32_bf16 v[108:111], v[68:71], v[172:175], v[108:111]
	global_load_dwordx4 v[52:55], v192, s[64:65] offset:-3072
	global_load_dwordx4 v[68:71], v192, s[64:65] offset:1024
	ds_read_b128 v[168:171], v197 offset:8896
	s_waitcnt lgkmcnt(6)
	s_waitcnt vmcnt(22)
	v_mfma_f32_16x16x32_bf16 v[80:83], v[56:59], v[144:147], v[80:83]
	v_mfma_f32_16x16x32_bf16 v[96:99], v[72:75], v[144:147], v[96:99]
	ds_read_b128 v[172:175], v197 offset:13248
	s_waitcnt lgkmcnt(6)
	v_mfma_f32_16x16x32_bf16 v[84:87], v[56:59], v[148:151], v[84:87]
	v_mfma_f32_16x16x32_bf16 v[100:103], v[72:75], v[148:151], v[100:103]
	s_waitcnt lgkmcnt(5)
	v_mfma_f32_16x16x32_bf16 v[88:91], v[56:59], v[152:155], v[88:91]
	v_mfma_f32_16x16x32_bf16 v[104:107], v[72:75], v[152:155], v[104:107]
	s_waitcnt lgkmcnt(4)
	v_mfma_f32_16x16x32_bf16 v[92:95], v[56:59], v[156:159], v[92:95]
	v_mfma_f32_16x16x32_bf16 v[108:111], v[72:75], v[156:159], v[108:111]
	global_load_dwordx4 v[56:59], v192, s[64:65] offset:-2048
	global_load_dwordx4 v[72:75], v192, s[64:65] offset:2048
	s_waitcnt lgkmcnt(3)
	s_waitcnt vmcnt(22)
	v_mfma_f32_16x16x32_bf16 v[80:83], v[60:63], v[160:163], v[80:83]
	v_mfma_f32_16x16x32_bf16 v[96:99], v[76:79], v[160:163], v[96:99]
	s_waitcnt lgkmcnt(2)
	v_mfma_f32_16x16x32_bf16 v[84:87], v[60:63], v[164:167], v[84:87]
	v_mfma_f32_16x16x32_bf16 v[100:103], v[76:79], v[164:167], v[100:103]
	s_waitcnt lgkmcnt(1)
	v_mfma_f32_16x16x32_bf16 v[88:91], v[60:63], v[168:171], v[88:91]
	v_mfma_f32_16x16x32_bf16 v[104:107], v[76:79], v[168:171], v[104:107]
	s_waitcnt lgkmcnt(0)
	v_mfma_f32_16x16x32_bf16 v[92:95], v[60:63], v[172:175], v[92:95]
	v_mfma_f32_16x16x32_bf16 v[108:111], v[76:79], v[172:175], v[108:111]
	global_load_dwordx4 v[60:63], v192, s[64:65] offset:-1024
	global_load_dwordx4 v[76:79], v192, s[64:65] offset:3072
	s_nop 7
	v_cvt_pk_bf16_f32 v144, v80, v81
	v_cvt_pk_bf16_f32 v145, v82, v83
	ds_write_b64 v200, v[144:145] offset:0
	v_cvt_pk_bf16_f32 v148, v84, v85
	v_cvt_pk_bf16_f32 v149, v86, v87
	ds_write_b64 v200, v[148:149] offset:8448
	v_cvt_pk_bf16_f32 v152, v88, v89
	v_cvt_pk_bf16_f32 v153, v90, v91
	ds_write_b64 v200, v[152:153] offset:16896
	v_cvt_pk_bf16_f32 v156, v92, v93
	v_cvt_pk_bf16_f32 v157, v94, v95
	ds_write_b64 v200, v[156:157] offset:25344
	v_cvt_pk_bf16_f32 v160, v96, v97
	v_cvt_pk_bf16_f32 v161, v98, v99
	ds_write_b64 v200, v[160:161] offset:32
	v_cvt_pk_bf16_f32 v164, v100, v101
	v_cvt_pk_bf16_f32 v165, v102, v103
	ds_write_b64 v200, v[164:165] offset:8480
	v_cvt_pk_bf16_f32 v168, v104, v105
	v_cvt_pk_bf16_f32 v169, v106, v107
	ds_write_b64 v200, v[168:169] offset:16928
	v_cvt_pk_bf16_f32 v172, v108, v109
	v_cvt_pk_bf16_f32 v173, v110, v111
	ds_write_b64 v200, v[172:173] offset:25376
	s_waitcnt vmcnt(46)
	ds_write_b128 v201, v[222:225]
	ds_write_b128 v201, v[226:229] offset:128
	v_add_u32_e32 v196, s80, v196
	v_subrev_u32_e32 v200, s80, v200
	v_add_u32_e32 v197, s81, v197
	v_subrev_u32_e32 v201, s81, v201
	s_sub_u32 s80, 0, s80
	s_sub_u32 s81, 0, s81
	s_add_u32 s68, s68, 0x80000
	s_addc_u32 s69, s69, 0
	s_add_u32 s70, s70, 1
	s_cmp_lt_u32 s70, 31
	s_cselect_b32 s83, 1, 0
	s_lshl_b32 s76, s83, 16
	s_add_u32 s64, s64, s76
	s_addc_u32 s65, s65, 0
	s_cmp_lt_u32 s70, 30
	s_cselect_b32 s83, 1, 0
	s_lshl_b32 s76, s83, 18
	s_add_u32 s60, s60, s76
	s_addc_u32 s61, s61, 0
	s_lshl_b32 s76, s83, 15
	s_add_u32 s62, s62, s76
	s_addc_u32 s63, s63, 0
	s_lshl_b32 s76, s83, 8
	s_add_u32 s66, s66, s76
	s_addc_u32 s67, s67, 0
	s_waitcnt lgkmcnt(0)
	s_barrier
	global_load_dwordx4 v[222:225], v194, s[66:67]
	global_load_dwordx4 v[226:229], v194, s[66:67] offset:128
	ds_read_b128 v[144:147], v196 offset:0
	ds_read_b128 v[148:151], v196 offset:8448
	ds_read_b128 v[152:155], v196 offset:16896
	ds_read_b128 v[156:159], v196 offset:25344
	ds_read_b128 v[160:163], v196 offset:64
	ds_read_b128 v[164:167], v196 offset:8512
	ds_read_b128 v[168:171], v196 offset:16960
	s_waitcnt lgkmcnt(6)
	s_waitcnt vmcnt(47)
	v_mfma_f32_16x16x32_bf16 v[112:115], v[144:147], v[230:233], 0
	ds_read_b128 v[172:175], v196 offset:25408
	s_waitcnt lgkmcnt(6)
	v_mfma_f32_16x16x32_bf16 v[116:119], v[148:151], v[230:233], 0
	ds_read_b128 v[144:147], v196 offset:128
	s_waitcnt lgkmcnt(6)
	v_mfma_f32_16x16x32_bf16 v[120:123], v[152:155], v[230:233], 0
	ds_read_b128 v[148:151], v196 offset:8576
	s_waitcnt lgkmcnt(6)
	v_mfma_f32_16x16x32_bf16 v[124:127], v[156:159], v[230:233], 0
	global_load_dwordx4 v[230:233], v193, s[60:61]
	ds_read_b128 v[152:155], v196 offset:17024
	s_waitcnt lgkmcnt(6)
	s_waitcnt vmcnt(47)
	v_mfma_f32_16x16x32_bf16 v[112:115], v[160:163], v[234:237], v[112:115]
	ds_read_b128 v[156:159], v196 offset:25472
	s_waitcnt lgkmcnt(6)
	v_mfma_f32_16x16x32_bf16 v[116:119], v[164:167], v[234:237], v[116:119]
	ds_read_b128 v[160:163], v196 offset:192
	s_waitcnt lgkmcnt(6)
	v_mfma_f32_16x16x32_bf16 v[120:123], v[168:171], v[234:237], v[120:123]
	ds_read_b128 v[164:167], v196 offset:8640
	s_waitcnt lgkmcnt(6)
	v_mfma_f32_16x16x32_bf16 v[124:127], v[172:175], v[234:237], v[124:127]
	global_load_dwordx4 v[234:237], v193, s[60:61] offset:64
	ds_read_b128 v[168:171], v196 offset:17088
	s_waitcnt lgkmcnt(6)
	s_waitcnt vmcnt(47)
	v_mfma_f32_16x16x32_bf16 v[112:115], v[144:147], v[238:241], v[112:115]
	ds_read_b128 v[172:175], v196 offset:25536
	s_waitcnt lgkmcnt(6)
	v_mfma_f32_16x16x32_bf16 v[116:119], v[148:151], v[238:241], v[116:119]
	ds_read_b128 v[144:147], v196 offset:256
	s_waitcnt lgkmcnt(6)
	v_mfma_f32_16x16x32_bf16 v[120:123], v[152:155], v[238:241], v[120:123]
	ds_read_b128 v[148:151], v196 offset:8704
	s_waitcnt lgkmcnt(6)
	v_mfma_f32_16x16x32_bf16 v[124:127], v[156:159], v[238:241], v[124:127]
	global_load_dwordx4 v[238:241], v193, s[60:61] offset:128
	ds_read_b128 v[152:155], v196 offset:17152
	s_waitcnt lgkmcnt(6)
	s_waitcnt vmcnt(47)
	v_mfma_f32_16x16x32_bf16 v[112:115], v[160:163], v[242:245], v[112:115]
	ds_read_b128 v[156:159], v196 offset:25600
	s_waitcnt lgkmcnt(6)
	v_mfma_f32_16x16x32_bf16 v[116:119], v[164:167], v[242:245], v[116:119]
	ds_read_b128 v[160:163], v196 offset:320
	s_waitcnt lgkmcnt(6)
	v_mfma_f32_16x16x32_bf16 v[120:123], v[168:171], v[242:245], v[120:123]
	ds_read_b128 v[164:167], v196 offset:8768
	s_waitcnt lgkmcnt(6)
	v_mfma_f32_16x16x32_bf16 v[124:127], v[172:175], v[242:245], v[124:127]
	global_load_dwordx4 v[242:245], v193, s[60:61] offset:192
	ds_read_b128 v[168:171], v196 offset:17216
	s_waitcnt lgkmcnt(6)
	s_waitcnt vmcnt(47)
	v_mfma_f32_16x16x32_bf16 v[112:115], v[144:147], v[246:249], v[112:115]
	ds_read_b128 v[172:175], v196 offset:25664
	s_waitcnt lgkmcnt(6)
	v_mfma_f32_16x16x32_bf16 v[116:119], v[148:151], v[246:249], v[116:119]
	ds_read_b128 v[144:147], v196 offset:384
	s_waitcnt lgkmcnt(6)
	v_mfma_f32_16x16x32_bf16 v[120:123], v[152:155], v[246:249], v[120:123]
	ds_read_b128 v[148:151], v196 offset:8832
	s_waitcnt lgkmcnt(6)
	v_mfma_f32_16x16x32_bf16 v[124:127], v[156:159], v[246:249], v[124:127]
	global_load_dwordx4 v[246:249], v193, s[60:61] offset:256
	ds_read_b128 v[152:155], v196 offset:17280
	s_waitcnt lgkmcnt(6)
	s_waitcnt vmcnt(47)
	v_mfma_f32_16x16x32_bf16 v[112:115], v[160:163], v[250:253], v[112:115]
	ds_read_b128 v[156:159], v196 offset:25728
	s_waitcnt lgkmcnt(6)
	v_mfma_f32_16x16x32_bf16 v[116:119], v[164:167], v[250:253], v[116:119]
	ds_read_b128 v[160:163], v196 offset:448
	s_waitcnt lgkmcnt(6)
	v_mfma_f32_16x16x32_bf16 v[120:123], v[168:171], v[250:253], v[120:123]
	ds_read_b128 v[164:167], v196 offset:8896
	s_waitcnt lgkmcnt(6)
	v_mfma_f32_16x16x32_bf16 v[124:127], v[172:175], v[250:253], v[124:127]
	global_load_dwordx4 v[250:253], v193, s[60:61] offset:320
	ds_read_b128 v[168:171], v196 offset:17344
	s_waitcnt lgkmcnt(6)
	s_waitcnt vmcnt(47)
	v_mfma_f32_16x16x32_bf16 v[112:115], v[144:147], v[184:187], v[112:115]
	ds_read_b128 v[172:175], v196 offset:25792
	s_waitcnt lgkmcnt(6)
	v_mfma_f32_16x16x32_bf16 v[116:119], v[148:151], v[184:187], v[116:119]
	s_waitcnt lgkmcnt(5)
	v_mfma_f32_16x16x32_bf16 v[120:123], v[152:155], v[184:187], v[120:123]
	s_waitcnt lgkmcnt(4)
	v_mfma_f32_16x16x32_bf16 v[124:127], v[156:159], v[184:187], v[124:127]
	global_load_dwordx4 v[184:187], v193, s[60:61] offset:384
	s_waitcnt lgkmcnt(3)
	s_waitcnt vmcnt(47)
	v_mfma_f32_16x16x32_bf16 v[112:115], v[160:163], v[188:191], v[112:115]
	s_waitcnt lgkmcnt(2)
	v_mfma_f32_16x16x32_bf16 v[116:119], v[164:167], v[188:191], v[116:119]
	s_waitcnt lgkmcnt(1)
	v_mfma_f32_16x16x32_bf16 v[120:123], v[168:171], v[188:191], v[120:123]
	s_waitcnt lgkmcnt(0)
	v_mfma_f32_16x16x32_bf16 v[124:127], v[172:175], v[188:191], v[124:127]
	global_load_dwordx4 v[188:191], v193, s[60:61] offset:448
	s_nop 7
	v_pk_mul_f32 v[112:113], v[112:113], v[202:203]
	v_pk_mul_f32 v[114:115], v[114:115], v[202:203]
	v_pk_mul_f32 v[116:117], v[116:117], v[202:203]
	v_pk_mul_f32 v[118:119], v[118:119], v[202:203]
	v_pk_mul_f32 v[120:121], v[120:121], v[202:203]
	v_pk_mul_f32 v[122:123], v[122:123], v[202:203]
	v_pk_mul_f32 v[124:125], v[124:125], v[202:203]
	v_pk_mul_f32 v[126:127], v[126:127], v[202:203]
	ds_read_b128 v[144:147], v197 offset:0
	ds_read_b128 v[148:151], v197 offset:4352
	ds_read_b128 v[152:155], v197 offset:8704
	ds_read_b128 v[156:159], v197 offset:13056
	ds_read_b128 v[160:163], v197 offset:64
	ds_read_b128 v[164:167], v197 offset:4416
	ds_read_b128 v[168:171], v197 offset:8768
	s_waitcnt lgkmcnt(6)
	s_waitcnt vmcnt(47)
	v_mfma_f32_16x16x32_bf16 v[112:115], v[144:147], v[128:131], v[112:115]
	ds_read_b128 v[172:175], v197 offset:13120
	s_waitcnt lgkmcnt(6)
	v_mfma_f32_16x16x32_bf16 v[116:119], v[148:151], v[128:131], v[116:119]
	ds_read_b128 v[144:147], v197 offset:128
	s_waitcnt lgkmcnt(6)
	v_mfma_f32_16x16x32_bf16 v[120:123], v[152:155], v[128:131], v[120:123]
	ds_read_b128 v[148:151], v197 offset:4480
	s_waitcnt lgkmcnt(6)
	v_mfma_f32_16x16x32_bf16 v[124:127], v[156:159], v[128:131], v[124:127]
	global_load_dwordx4 v[128:131], v192, s[62:63]
	ds_read_b128 v[152:155], v197 offset:8832
	s_waitcnt lgkmcnt(6)
	s_waitcnt vmcnt(47)
	v_mfma_f32_16x16x32_bf16 v[112:115], v[160:163], v[132:135], v[112:115]
	ds_read_b128 v[156:159], v197 offset:13184
	s_waitcnt lgkmcnt(6)
	v_mfma_f32_16x16x32_bf16 v[116:119], v[164:167], v[132:135], v[116:119]
	ds_read_b128 v[160:163], v197 offset:192
	s_waitcnt lgkmcnt(6)
	v_mfma_f32_16x16x32_bf16 v[120:123], v[168:171], v[132:135], v[120:123]
	ds_read_b128 v[164:167], v197 offset:4544
	s_waitcnt lgkmcnt(6)
	v_mfma_f32_16x16x32_bf16 v[124:127], v[172:175], v[132:135], v[124:127]
	global_load_dwordx4 v[132:135], v192, s[62:63] offset:1024
	ds_read_b128 v[168:171], v197 offset:8896
	s_waitcnt lgkmcnt(6)
	s_waitcnt vmcnt(47)
	v_mfma_f32_16x16x32_bf16 v[112:115], v[144:147], v[136:139], v[112:115]
	ds_read_b128 v[172:175], v197 offset:13248
	s_waitcnt lgkmcnt(6)
	v_mfma_f32_16x16x32_bf16 v[116:119], v[148:151], v[136:139], v[116:119]
	s_waitcnt lgkmcnt(5)
	v_mfma_f32_16x16x32_bf16 v[120:123], v[152:155], v[136:139], v[120:123]
	s_waitcnt lgkmcnt(4)
	v_mfma_f32_16x16x32_bf16 v[124:127], v[156:159], v[136:139], v[124:127]
	global_load_dwordx4 v[136:139], v192, s[62:63] offset:2048
	s_waitcnt lgkmcnt(3)
	s_waitcnt vmcnt(47)
	v_mfma_f32_16x16x32_bf16 v[112:115], v[160:163], v[140:143], v[112:115]
	s_waitcnt lgkmcnt(2)
	v_mfma_f32_16x16x32_bf16 v[116:119], v[164:167], v[140:143], v[116:119]
	s_waitcnt lgkmcnt(1)
	v_mfma_f32_16x16x32_bf16 v[120:123], v[168:171], v[140:143], v[120:123]
	s_waitcnt lgkmcnt(0)
	v_mfma_f32_16x16x32_bf16 v[124:127], v[172:175], v[140:143], v[124:127]
	global_load_dwordx4 v[140:143], v192, s[62:63] offset:3072
	s_nop 7
	v_cvt_pk_bf16_f32 v160, v112, v113
	v_cvt_pk_bf16_f32 v161, v114, v115
	v_cvt_pk_bf16_f32 v162, v116, v117
	v_cvt_pk_bf16_f32 v163, v118, v119
	v_cvt_pk_bf16_f32 v164, v120, v121
	v_cvt_pk_bf16_f32 v165, v122, v123
	v_cvt_pk_bf16_f32 v166, v124, v125
	v_cvt_pk_bf16_f32 v167, v126, v127
	ds_write_b64 v214, v[160:161]
	ds_write_b64 v214, v[162:163] offset:32
	ds_write_b64 v214, v[164:165] offset:64
	ds_write_b64 v214, v[166:167] offset:96
	s_waitcnt lgkmcnt(0)
	ds_read_b128 v[144:147], v215
	ds_read_b128 v[148:151], v215 offset:1152
	s_waitcnt lgkmcnt(0)
	global_store_dwordx4 v195, v[144:147], s[68:69]
	global_store_dwordx4 v220, v[148:151], s[68:69]
	v_pk_mul_f32 v[80:81], v[80:81], v[204:205]
	v_pk_mul_f32 v[82:83], v[82:83], v[204:205]
	v_pk_mul_f32 v[84:85], v[84:85], v[204:205]
	v_pk_mul_f32 v[86:87], v[86:87], v[204:205]
	v_pk_mul_f32 v[88:89], v[88:89], v[204:205]
	v_pk_mul_f32 v[90:91], v[90:91], v[204:205]
	v_pk_mul_f32 v[92:93], v[92:93], v[204:205]
	v_pk_mul_f32 v[94:95], v[94:95], v[204:205]
	v_pk_mul_f32 v[96:97], v[96:97], v[204:205]
	v_pk_mul_f32 v[98:99], v[98:99], v[204:205]
	v_pk_mul_f32 v[100:101], v[100:101], v[204:205]
	v_pk_mul_f32 v[102:103], v[102:103], v[204:205]
	v_pk_mul_f32 v[104:105], v[104:105], v[204:205]
	v_pk_mul_f32 v[106:107], v[106:107], v[204:205]
	v_pk_mul_f32 v[108:109], v[108:109], v[204:205]
	v_pk_mul_f32 v[110:111], v[110:111], v[204:205]
	ds_read_b128 v[144:147], v197 offset:0
	ds_read_b128 v[148:151], v197 offset:4352
	ds_read_b128 v[152:155], v197 offset:8704
	ds_read_b128 v[156:159], v197 offset:13056
	ds_read_b128 v[160:163], v197 offset:64
	ds_read_b128 v[164:167], v197 offset:4416
	ds_read_b128 v[168:171], v197 offset:8768
	s_waitcnt lgkmcnt(6)
	s_waitcnt vmcnt(22)
	v_mfma_f32_16x16x32_bf16 v[80:83], v[48:51], v[144:147], v[80:83]
	v_mfma_f32_16x16x32_bf16 v[96:99], v[64:67], v[144:147], v[96:99]
	ds_read_b128 v[172:175], v197 offset:13120
	s_waitcnt lgkmcnt(6)
	v_mfma_f32_16x16x32_bf16 v[84:87], v[48:51], v[148:151], v[84:87]
	v_mfma_f32_16x16x32_bf16 v[100:103], v[64:67], v[148:151], v[100:103]
	ds_read_b128 v[144:147], v197 offset:128
	s_waitcnt lgkmcnt(6)
	v_mfma_f32_16x16x32_bf16 v[88:91], v[48:51], v[152:155], v[88:91]
	v_mfma_f32_16x16x32_bf16 v[104:107], v[64:67], v[152:155], v[104:107]
	ds_read_b128 v[148:151], v197 offset:4480
	s_waitcnt lgkmcnt(6)
	v_mfma_f32_16x16x32_bf16 v[92:95], v[48:51], v[156:159], v[92:95]
	v_mfma_f32_16x16x32_bf16 v[108:111], v[64:67], v[156:159], v[108:111]
	global_load_dwordx4 v[48:51], v192, s[64:65] offset:-4096
	global_load_dwordx4 v[64:67], v192, s[64:65]
	ds_read_b128 v[152:155], v197 offset:8832
	s_waitcnt lgkmcnt(6)
	s_waitcnt vmcnt(22)
	v_mfma_f32_16x16x32_bf16 v[80:83], v[52:55], v[160:163], v[80:83]
	v_mfma_f32_16x16x32_bf16 v[96:99], v[68:71], v[160:163], v[96:99]
	ds_read_b128 v[156:159], v197 offset:13184
	s_waitcnt lgkmcnt(6)
	v_mfma_f32_16x16x32_bf16 v[84:87], v[52:55], v[164:167], v[84:87]
	v_mfma_f32_16x16x32_bf16 v[100:103], v[68:71], v[164:167], v[100:103]
	ds_read_b128 v[160:163], v197 offset:192
	s_waitcnt lgkmcnt(6)
	v_mfma_f32_16x16x32_bf16 v[88:91], v[52:55], v[168:171], v[88:91]
	v_mfma_f32_16x16x32_bf16 v[104:107], v[68:71], v[168:171], v[104:107]
	ds_read_b128 v[164:167], v197 offset:4544
	s_waitcnt lgkmcnt(6)
	v_mfma_f32_16x16x32_bf16 v[92:95], v[52:55], v[172:175], v[92:95]
	v_mfma_f32_16x16x32_bf16 v[108:111], v[68:71], v[172:175], v[108:111]
	global_load_dwordx4 v[52:55], v192, s[64:65] offset:-3072
	global_load_dwordx4 v[68:71], v192, s[64:65] offset:1024
	ds_read_b128 v[168:171], v197 offset:8896
	s_waitcnt lgkmcnt(6)
	s_waitcnt vmcnt(22)
	v_mfma_f32_16x16x32_bf16 v[80:83], v[56:59], v[144:147], v[80:83]
	v_mfma_f32_16x16x32_bf16 v[96:99], v[72:75], v[144:147], v[96:99]
	ds_read_b128 v[172:175], v197 offset:13248
	s_waitcnt lgkmcnt(6)
	v_mfma_f32_16x16x32_bf16 v[84:87], v[56:59], v[148:151], v[84:87]
	v_mfma_f32_16x16x32_bf16 v[100:103], v[72:75], v[148:151], v[100:103]
	s_waitcnt lgkmcnt(5)
	v_mfma_f32_16x16x32_bf16 v[88:91], v[56:59], v[152:155], v[88:91]
	v_mfma_f32_16x16x32_bf16 v[104:107], v[72:75], v[152:155], v[104:107]
	s_waitcnt lgkmcnt(4)
	v_mfma_f32_16x16x32_bf16 v[92:95], v[56:59], v[156:159], v[92:95]
	v_mfma_f32_16x16x32_bf16 v[108:111], v[72:75], v[156:159], v[108:111]
	global_load_dwordx4 v[56:59], v192, s[64:65] offset:-2048
	global_load_dwordx4 v[72:75], v192, s[64:65] offset:2048
	s_waitcnt lgkmcnt(3)
	s_waitcnt vmcnt(22)
	v_mfma_f32_16x16x32_bf16 v[80:83], v[60:63], v[160:163], v[80:83]
	v_mfma_f32_16x16x32_bf16 v[96:99], v[76:79], v[160:163], v[96:99]
	s_waitcnt lgkmcnt(2)
	v_mfma_f32_16x16x32_bf16 v[84:87], v[60:63], v[164:167], v[84:87]
	v_mfma_f32_16x16x32_bf16 v[100:103], v[76:79], v[164:167], v[100:103]
	s_waitcnt lgkmcnt(1)
	v_mfma_f32_16x16x32_bf16 v[88:91], v[60:63], v[168:171], v[88:91]
	v_mfma_f32_16x16x32_bf16 v[104:107], v[76:79], v[168:171], v[104:107]
	s_waitcnt lgkmcnt(0)
	v_mfma_f32_16x16x32_bf16 v[92:95], v[60:63], v[172:175], v[92:95]
	v_mfma_f32_16x16x32_bf16 v[108:111], v[76:79], v[172:175], v[108:111]
	global_load_dwordx4 v[60:63], v192, s[64:65] offset:-1024
	global_load_dwordx4 v[76:79], v192, s[64:65] offset:3072
	s_nop 7
	v_cvt_pk_bf16_f32 v144, v80, v81
	v_cvt_pk_bf16_f32 v145, v82, v83
	ds_write_b64 v200, v[144:145] offset:0
	v_cvt_pk_bf16_f32 v148, v84, v85
	v_cvt_pk_bf16_f32 v149, v86, v87
	ds_write_b64 v200, v[148:149] offset:8448
	v_cvt_pk_bf16_f32 v152, v88, v89
	v_cvt_pk_bf16_f32 v153, v90, v91
	ds_write_b64 v200, v[152:153] offset:16896
	v_cvt_pk_bf16_f32 v156, v92, v93
	v_cvt_pk_bf16_f32 v157, v94, v95
	ds_write_b64 v200, v[156:157] offset:25344
	v_cvt_pk_bf16_f32 v160, v96, v97
	v_cvt_pk_bf16_f32 v161, v98, v99
	ds_write_b64 v200, v[160:161] offset:32
	v_cvt_pk_bf16_f32 v164, v100, v101
	v_cvt_pk_bf16_f32 v165, v102, v103
	ds_write_b64 v200, v[164:165] offset:8480
	v_cvt_pk_bf16_f32 v168, v104, v105
	v_cvt_pk_bf16_f32 v169, v106, v107
	ds_write_b64 v200, v[168:169] offset:16928
	v_cvt_pk_bf16_f32 v172, v108, v109
	v_cvt_pk_bf16_f32 v173, v110, v111
	ds_write_b64 v200, v[172:173] offset:25376
	s_waitcnt vmcnt(46)
	ds_write_b128 v201, v[176:179]
	ds_write_b128 v201, v[180:183] offset:128
	v_add_u32_e32 v196, s80, v196
	v_subrev_u32_e32 v200, s80, v200
	v_add_u32_e32 v197, s81, v197
	v_subrev_u32_e32 v201, s81, v201
	s_sub_u32 s80, 0, s80
	s_sub_u32 s81, 0, s81
	s_add_u32 s68, s68, 0x80000
	s_addc_u32 s69, s69, 0
	s_add_u32 s70, s70, 1
	s_cmp_lt_u32 s70, 31
	s_cselect_b32 s83, 1, 0
	s_lshl_b32 s76, s83, 16
	s_add_u32 s64, s64, s76
	s_addc_u32 s65, s65, 0
	s_cmp_lt_u32 s70, 30
	s_cselect_b32 s83, 1, 0
	s_lshl_b32 s76, s83, 18
	s_add_u32 s60, s60, s76
	s_addc_u32 s61, s61, 0
	s_lshl_b32 s76, s83, 15
	s_add_u32 s62, s62, s76
	s_addc_u32 s63, s63, 0
	s_lshl_b32 s76, s83, 8
	s_add_u32 s66, s66, s76
	s_addc_u32 s67, s67, 0
	s_waitcnt lgkmcnt(0)
	s_barrier
	s_cmp_lt_u32 s70, 32
	s_cbranch_scc1 .Lscan_chunk
	s_setprio 0
	s_waitcnt vmcnt(0)
	s_mov_b64 s[76:77], vcc
	v_and_b32_e32 v210, 2, v198
	v_cmp_eq_u32_e32 vcc, 0, v210
	s_nop 1
	v_cndmask_b32_dpp v144, v88, v80, vcc quad_perm:[2,3,0,1] row_mask:0xf bank_mask:0xf
	v_cndmask_b32_dpp v145, v92, v84, vcc quad_perm:[2,3,0,1] row_mask:0xf bank_mask:0xf
	v_cndmask_b32_dpp v148, v89, v81, vcc quad_perm:[2,3,0,1] row_mask:0xf bank_mask:0xf
	v_cndmask_b32_dpp v149, v93, v85, vcc quad_perm:[2,3,0,1] row_mask:0xf bank_mask:0xf
	v_cndmask_b32_dpp v152, v90, v82, vcc quad_perm:[2,3,0,1] row_mask:0xf bank_mask:0xf
	v_cndmask_b32_dpp v153, v94, v86, vcc quad_perm:[2,3,0,1] row_mask:0xf bank_mask:0xf
	v_cndmask_b32_dpp v156, v91, v83, vcc quad_perm:[2,3,0,1] row_mask:0xf bank_mask:0xf
	v_cndmask_b32_dpp v157, v95, v87, vcc quad_perm:[2,3,0,1] row_mask:0xf bank_mask:0xf
	v_cndmask_b32_dpp v160, v104, v96, vcc quad_perm:[2,3,0,1] row_mask:0xf bank_mask:0xf
	v_cndmask_b32_dpp v161, v108, v100, vcc quad_perm:[2,3,0,1] row_mask:0xf bank_mask:0xf
	v_cndmask_b32_dpp v164, v105, v97, vcc quad_perm:[2,3,0,1] row_mask:0xf bank_mask:0xf
	v_cndmask_b32_dpp v165, v109, v101, vcc quad_perm:[2,3,0,1] row_mask:0xf bank_mask:0xf
	v_cndmask_b32_dpp v168, v106, v98, vcc quad_perm:[2,3,0,1] row_mask:0xf bank_mask:0xf
	v_cndmask_b32_dpp v169, v110, v102, vcc quad_perm:[2,3,0,1] row_mask:0xf bank_mask:0xf
	v_cndmask_b32_dpp v172, v107, v99, vcc quad_perm:[2,3,0,1] row_mask:0xf bank_mask:0xf
	v_cndmask_b32_dpp v173, v111, v103, vcc quad_perm:[2,3,0,1] row_mask:0xf bank_mask:0xf
	s_not_b64 vcc, vcc
	s_nop 1
	v_cndmask_b32_dpp v146, v80, v88, vcc quad_perm:[2,3,0,1] row_mask:0xf bank_mask:0xf
	v_cndmask_b32_dpp v147, v84, v92, vcc quad_perm:[2,3,0,1] row_mask:0xf bank_mask:0xf
	v_cndmask_b32_dpp v150, v81, v89, vcc quad_perm:[2,3,0,1] row_mask:0xf bank_mask:0xf
	v_cndmask_b32_dpp v151, v85, v93, vcc quad_perm:[2,3,0,1] row_mask:0xf bank_mask:0xf
	v_cndmask_b32_dpp v154, v82, v90, vcc quad_perm:[2,3,0,1] row_mask:0xf bank_mask:0xf
	v_cndmask_b32_dpp v155, v86, v94, vcc quad_perm:[2,3,0,1] row_mask:0xf bank_mask:0xf
	v_cndmask_b32_dpp v158, v83, v91, vcc quad_perm:[2,3,0,1] row_mask:0xf bank_mask:0xf
	v_cndmask_b32_dpp v159, v87, v95, vcc quad_perm:[2,3,0,1] row_mask:0xf bank_mask:0xf
	v_cndmask_b32_dpp v162, v96, v104, vcc quad_perm:[2,3,0,1] row_mask:0xf bank_mask:0xf
	v_cndmask_b32_dpp v163, v100, v108, vcc quad_perm:[2,3,0,1] row_mask:0xf bank_mask:0xf
	v_cndmask_b32_dpp v166, v97, v105, vcc quad_perm:[2,3,0,1] row_mask:0xf bank_mask:0xf
	v_cndmask_b32_dpp v167, v101, v109, vcc quad_perm:[2,3,0,1] row_mask:0xf bank_mask:0xf
	v_cndmask_b32_dpp v170, v98, v106, vcc quad_perm:[2,3,0,1] row_mask:0xf bank_mask:0xf
	v_cndmask_b32_dpp v171, v102, v110, vcc quad_perm:[2,3,0,1] row_mask:0xf bank_mask:0xf
	v_cndmask_b32_dpp v174, v99, v107, vcc quad_perm:[2,3,0,1] row_mask:0xf bank_mask:0xf
	v_cndmask_b32_dpp v175, v103, v111, vcc quad_perm:[2,3,0,1] row_mask:0xf bank_mask:0xf
	v_and_b32_e32 v210, 1, v198
	v_cmp_eq_u32_e32 vcc, 0, v210
	s_nop 1
	v_cndmask_b32_dpp v0, v145, v144, vcc quad_perm:[1,0,3,2] row_mask:0xf bank_mask:0xf
	v_cndmask_b32_dpp v2, v147, v146, vcc quad_perm:[1,0,3,2] row_mask:0xf bank_mask:0xf
	v_cndmask_b32_dpp v4, v149, v148, vcc quad_perm:[1,0,3,2] row_mask:0xf bank_mask:0xf
	v_cndmask_b32_dpp v6, v151, v150, vcc quad_perm:[1,0,3,2] row_mask:0xf bank_mask:0xf
	v_cndmask_b32_dpp v8, v153, v152, vcc quad_perm:[1,0,3,2] row_mask:0xf bank_mask:0xf
	v_cndmask_b32_dpp v10, v155, v154, vcc quad_perm:[1,0,3,2] row_mask:0xf bank_mask:0xf
	v_cndmask_b32_dpp v12, v157, v156, vcc quad_perm:[1,0,3,2] row_mask:0xf bank_mask:0xf
	v_cndmask_b32_dpp v14, v159, v158, vcc quad_perm:[1,0,3,2] row_mask:0xf bank_mask:0xf
	v_cndmask_b32_dpp v16, v161, v160, vcc quad_perm:[1,0,3,2] row_mask:0xf bank_mask:0xf
	v_cndmask_b32_dpp v18, v163, v162, vcc quad_perm:[1,0,3,2] row_mask:0xf bank_mask:0xf
	v_cndmask_b32_dpp v20, v165, v164, vcc quad_perm:[1,0,3,2] row_mask:0xf bank_mask:0xf
	v_cndmask_b32_dpp v22, v167, v166, vcc quad_perm:[1,0,3,2] row_mask:0xf bank_mask:0xf
	v_cndmask_b32_dpp v24, v169, v168, vcc quad_perm:[1,0,3,2] row_mask:0xf bank_mask:0xf
	v_cndmask_b32_dpp v26, v171, v170, vcc quad_perm:[1,0,3,2] row_mask:0xf bank_mask:0xf
	v_cndmask_b32_dpp v28, v173, v172, vcc quad_perm:[1,0,3,2] row_mask:0xf bank_mask:0xf
	v_cndmask_b32_dpp v30, v175, v174, vcc quad_perm:[1,0,3,2] row_mask:0xf bank_mask:0xf
	s_not_b64 vcc, vcc
	s_nop 1
	v_cndmask_b32_dpp v1, v144, v145, vcc quad_perm:[1,0,3,2] row_mask:0xf bank_mask:0xf
	v_cndmask_b32_dpp v3, v146, v147, vcc quad_perm:[1,0,3,2] row_mask:0xf bank_mask:0xf
	v_cndmask_b32_dpp v5, v148, v149, vcc quad_perm:[1,0,3,2] row_mask:0xf bank_mask:0xf
	v_cndmask_b32_dpp v7, v150, v151, vcc quad_perm:[1,0,3,2] row_mask:0xf bank_mask:0xf
	v_cndmask_b32_dpp v9, v152, v153, vcc quad_perm:[1,0,3,2] row_mask:0xf bank_mask:0xf
	v_cndmask_b32_dpp v11, v154, v155, vcc quad_perm:[1,0,3,2] row_mask:0xf bank_mask:0xf
	v_cndmask_b32_dpp v13, v156, v157, vcc quad_perm:[1,0,3,2] row_mask:0xf bank_mask:0xf
	v_cndmask_b32_dpp v15, v158, v159, vcc quad_perm:[1,0,3,2] row_mask:0xf bank_mask:0xf
	v_cndmask_b32_dpp v17, v160, v161, vcc quad_perm:[1,0,3,2] row_mask:0xf bank_mask:0xf
	v_cndmask_b32_dpp v19, v162, v163, vcc quad_perm:[1,0,3,2] row_mask:0xf bank_mask:0xf
	v_cndmask_b32_dpp v21, v164, v165, vcc quad_perm:[1,0,3,2] row_mask:0xf bank_mask:0xf
	v_cndmask_b32_dpp v23, v166, v167, vcc quad_perm:[1,0,3,2] row_mask:0xf bank_mask:0xf
	v_cndmask_b32_dpp v25, v168, v169, vcc quad_perm:[1,0,3,2] row_mask:0xf bank_mask:0xf
	v_cndmask_b32_dpp v27, v170, v171, vcc quad_perm:[1,0,3,2] row_mask:0xf bank_mask:0xf
	v_cndmask_b32_dpp v29, v172, v173, vcc quad_perm:[1,0,3,2] row_mask:0xf bank_mask:0xf
	v_cndmask_b32_dpp v31, v174, v175, vcc quad_perm:[1,0,3,2] row_mask:0xf bank_mask:0xf
	s_mov_b64 vcc, s[76:77]
	global_store_dwordx4 v206, v[0:3], s[44:45]
	global_store_dwordx4 v207, v[4:7], s[44:45]
	global_store_dwordx4 v208, v[8:11], s[44:45]
	global_store_dwordx4 v209, v[12:15], s[44:45]
	global_store_dwordx4 v206, v[16:19], s[46:47]
	global_store_dwordx4 v207, v[20:23], s[46:47]
	global_store_dwordx4 v208, v[24:27], s[46:47]
	global_store_dwordx4 v209, v[28:31], s[46:47]
